# P2 balance: sample-conv units on CUs with pool-mix group 0/1, new-state row copies on CUs with group 2/3
# speedup vs baseline: 1.1221x; 1.0003x over previous
; #define LAS __attribute__((address_space(3)))
; __device__ __forceinline__ void p2_conv_unit_sample(Frame& F, int bs, const ConvW& cw) {
;     LAS float* Y = (LAS float*)F.lds;
;     unsigned p = 192u * (unsigned)F.wave + 2u * (unsigned)F.lane, q = 192u * (unsigned)F.wave + 128u + (unsigned)F.lane;
;     asm volatile("" : "+v"(p), "+v"(q));
;     f32x2 wp[CW]; float wq[CW];
; #pragma unroll
;     for (int j = 0; j < CW; ++j) { wp[j] = cw.wp[j]; wq[j] = cw.wq[j]; }
;     const f32x2 bp = cw.bp; const float bq = cw.bq;
;     const int rowA = MP + bs * DS;
;     conv_block16<true, 1>(F, rowA, wp, wq, bp, bq, Y);
; __device__ __forceinline__ void p2_mixers(LAS unsigned char* lds, const ConvW& cw) {
;     ...
;     { Frame F = make_frame(lds); for (int bs = (F.vcu + F.G - 64) % F.G; bs < DB; bs += F.G) p2_conv_unit_sample(F, bs, cw); }
.LBB0_446:
	s_mov_b32 s99, s8
	s_abs_i32 s29, s3
	v_cvt_f32_u32_e32 v1, s29
	s_add_i32 s8, s3, s8
	s_sub_i32 s9, s8, 64
	s_sub_i32 s8, 64, s8
	v_rcp_iflag_f32_e32 v1, v1
	s_ashr_i32 s40, s9, 31
	s_max_i32 s8, s9, s8
	s_sub_i32 s9, 0, s29
	v_mul_f32_e32 v1, 0x4f7ffffe, v1
	v_cvt_u32_f32_e32 v1, v1
	s_mov_b64 s[6:7], s[0:1]
	v_readfirstlane_b32 s44, v1
	s_mul_i32 s9, s9, s44
	s_mul_hi_u32 s9, s44, s9
	s_add_i32 s44, s44, s9
	s_mul_hi_u32 s9, s8, s44
	s_mul_i32 s9, s9, s29
	s_sub_i32 s8, s8, s9
	s_sub_i32 s9, s8, s29
	s_cmp_ge_u32 s8, s29
	s_cselect_b32 s8, s9, s8
	s_sub_i32 s9, s8, s29
	s_cmp_ge_u32 s8, s29
	s_cselect_b32 s8, s9, s8
	s_xor_b32 s41, s8, s40
	s_sub_i32 s22, s41, s40
	s_lshr_b32 s22, s99, 2
	s_lshl_b32 s22, s22, 1
	s_and_b32 s100, s99, 1
	s_or_b32 s22, s22, s100
	s_bitcmp1_b32 s99, 1
	s_cselect_b32 s22, 0xff, s22
	s_mov_b32 s41, s22
	s_mov_b32 s40, 0
	s_cmpk_gt_i32 s22, 0x7f
	s_cbranch_scc1 .LBB0_452
	s_load_dwordx2 s[18:19], s[6:7], 0x30
	s_load_dwordx4 s[8:11], s[6:7], 0x80
	s_ashr_i32 s36, s12, 6
	s_load_dwordx2 s[6:7], s[6:7], 0xb0
	s_mul_i32 s23, s36, 0xc0
	s_add_i32 s24, s23, 0x80
	v_and_b32_e32 v134, 63, v2
	v_lshl_add_u32 v135, v134, 1, s23
	s_waitcnt lgkmcnt(0)
	s_add_u32 s25, s6, 0x5e00000
	s_addc_u32 s26, s7, 0
	s_add_u32 s27, s6, 0xd200000
	s_addc_u32 s34, s7, 0
	s_cmp_lt_i32 s36, 2
	s_cselect_b64 s[12:13], -1, 0
	s_lshl_b32 s35, s36, 1
	s_or_b32 s37, s35, 1
	s_cmp_lt_i32 s37, 4
	s_mul_i32 s7, s22, 0x2d000
	s_cselect_b64 s[16:17], -1, 0
	s_mul_hi_i32 s6, s22, 0x2d000
	s_add_u32 s7, s18, s7
	s_addc_u32 s6, s19, s6
	s_add_u32 s18, s7, 0x2b800
	s_addc_u32 s19, s6, 0
	s_lshl_b32 s6, s41, 2
	s_lshl_b32 s7, s40, 2
	s_sub_i32 s6, s6, s7
	v_or_b32_e32 v136, s24, v134
	s_mulk_i32 s36, 0x3000
	s_mulk_i32 s37, 0x1800
	s_mul_hi_i32 s38, s3, 0x2d000
	s_mul_i32 s39, s3, 0x2d000
	s_add_i32 s40, s6, 0x2003
	s_lshl_b32 s41, s3, 2
	v_mov_b32_e32 v33, 0
	v_mov_b32_e32 v137, 0x358637bd
	s_mov_b32 s42, 0xf800000
	v_mov_b32_e32 v138, 0x260
	v_mov_b32_e32 v139, 0xba2aaaab
	v_mov_b32_e32 v140, 0x3a2aaaab
	s_branch .LBB0_449

; #define GAS __attribute__((address_space(1)))
; __device__ __forceinline__ float bf_lo(unsigned w) { return __uint_as_float(w << 16); }
; __device__ __forceinline__ float bf_hi(unsigned w) { return __uint_as_float(w & 0xffff0000u); }
; __device__ __forceinline__ void p2_states(Frame& F) {
;     const bf16_t* U = WSP(bf16_t, WS_U); const bf16_t* A = WSP(bf16_t, WS_A);
;     constexpr int R_PSP = NB * PSTATE, R_CSP = NB * CSTATE, R_S = DB * DS;
;     const unsigned ln = (unsigned)F.lane;
;     for (int i = F.vcu * NWAVES + F.wave; i < R_PSP + R_CSP + 2 * R_S; i += F.G * NWAVES) {
;         int r = i; const bf16_t* sb; float* dst;
;         if (r < R_PSP) { const int j = r % PSTATE, b = r / PSTATE; sb = U + (size_t)(b * SEQ + SEQ - PSTATE + j) * DPOOL; dst = F.out + O_PSP + (size_t)r * DPOOL; }
;         else if ((r -= R_PSP) < R_CSP) { const int j = r % CSTATE, b = r / CSTATE; sb = A + (size_t)(b * SEQ + SEQ - CSTATE + j) * DCONV; dst = F.out + O_CSP + (size_t)r * DCONV; }
;         else if ((r -= R_CSP) < R_S) { const int b = r >> 2, t = r & 3; sb = U + (size_t)(MP + r) * DPOOL; dst = F.out + O_PSS + (size_t)(b * PSTATE + PSTATE - DS + t) * DPOOL; }
;         else { r -= R_S; const int b = r >> 2, t = r & 3; sb = A + (size_t)(MP + r) * DCONV; dst = F.out + O_CSS + (size_t)(b * CSTATE + CSTATE - DS + t) * DCONV; }
;         f32x4 v[6];
; #pragma unroll
;         for (int k = 0; k < 6; ++k) { const u32x2 w = ldg<u32x2>(sb, (256u * k + 4u * ln) * 2u); v[k] = (f32x4){bf_lo(w.x), bf_hi(w.x), bf_lo(w.y), bf_hi(w.y)}; }
; #pragma unroll
;         for (int k = 0; k < 6; ++k) *(GAS f32x4*)((char*)dst + (256u * k + 4u * ln) * 4u) = v[k];
;     }
; }
; __device__ __forceinline__ void p2_mixers(LAS unsigned char* lds, const ConvW& cw) {
;     ...
;     { Frame F = make_frame(lds); p2_states(F); if ((int)gridDim.x != 256) states_copy_rows(F, F.vcu * NWAVES + F.wave, F.G * NWAVES); }
.LBB0_543:
	s_mov_b64 s[12:13], s[0:1]
	s_load_dwordx4 s[8:11], s[12:13], 0x28
	s_load_dwordx4 s[16:19], s[12:13], 0xa8
	s_ashr_i32 s7, s24, 6
	s_bitcmp1_b32 s6, 1
	s_cbranch_scc0 .LBB0_558
	s_and_b32 s100, s6, 1
	s_lshr_b32 s6, s6, 2
	s_lshl_b32 s6, s6, 1
	s_or_b32 s6, s6, s100
	s_lshl_b32 s6, s6, 3
	v_and_b32_e32 v3, 63, v2
	s_add_i32 s29, s6, s7
	s_cmpk_gt_i32 s29, 0x4b3
	v_lshlrev_b32_e32 v2, 4, v3
	s_cbranch_scc1 .LBB0_558
	s_waitcnt lgkmcnt(0)
	s_add_u32 s34, s18, 0x2a00000
	s_addc_u32 s35, s19, 0
	s_add_u32 s36, s18, 0x5e00000
	s_addc_u32 s37, s19, 0
	s_add_u32 s6, s16, 0x9c4e000
	s_addc_u32 s7, s17, 0
	s_add_u32 s12, s16, 0x910e000
	s_addc_u32 s13, s17, 0
	s_add_u32 s18, s16, 0x905a000
	s_addc_u32 s19, s17, 0
	s_add_u32 s22, s16, 0x9000000
	v_mov_b32_e32 v5, 0
	s_addc_u32 s23, s17, 0
	s_bfe_u32 s47, s24, 0x20006
	v_lshlrev_b32_e32 v4, 3, v3
	v_mov_b32_e32 v3, v5
	s_add_i32 s46, s47, 26
	s_add_i32 s47, s47, 11
	s_mul_i32 s48, s29, 0xc00
	s_mov_b32 s49, 0x300000
	s_mov_b32 s25, 0
	s_mov_b32 s26, s29
	s_branch .LBB0_546
.LBB0_545:
	v_lshl_add_u64 v[6:7], s[38:39], 0, v[4:5]
	global_load_dwordx2 v[8:9], v[6:7], off
	global_load_dwordx2 v[12:13], v[6:7], off offset:512
	global_load_dwordx2 v[16:17], v[6:7], off offset:1024
	global_load_dwordx2 v[20:21], v[6:7], off offset:1536
	global_load_dwordx2 v[24:25], v[6:7], off offset:2048
	global_load_dwordx2 v[28:29], v[6:7], off offset:2560
	s_mul_i32 s24, s41, 0x1800
	s_mul_hi_u32 s27, s40, 0x1800
	s_mul_i32 s38, s40, 0x1800
	s_add_i32 s27, s27, s24
	s_add_u32 s38, s42, s38
	s_addc_u32 s39, s43, s27
	s_addk_i32 s26, 0x400
	s_add_i32 s48, s48, s49
	v_lshl_add_u64 v[30:31], s[38:39], 0, v[2:3]
	s_cmpk_lt_i32 s26, 0x4b4
	v_add_co_u32_e32 v32, vcc, 0x1000, v30
	s_waitcnt vmcnt(5)
	v_lshlrev_b32_e32 v6, 16, v8
	v_and_b32_e32 v7, 0xffff0000, v8
	v_lshlrev_b32_e32 v8, 16, v9
	v_and_b32_e32 v9, 0xffff0000, v9
	v_addc_co_u32_e32 v33, vcc, 0, v31, vcc
	s_waitcnt vmcnt(4)
	v_lshlrev_b32_e32 v10, 16, v12
	v_and_b32_e32 v11, 0xffff0000, v12
	v_lshlrev_b32_e32 v12, 16, v13
	v_and_b32_e32 v13, 0xffff0000, v13
	s_waitcnt vmcnt(3)
	v_lshlrev_b32_e32 v14, 16, v16
	v_and_b32_e32 v15, 0xffff0000, v16
	v_lshlrev_b32_e32 v16, 16, v17
	v_and_b32_e32 v17, 0xffff0000, v17
	s_waitcnt vmcnt(2)
	v_lshlrev_b32_e32 v18, 16, v20
	v_and_b32_e32 v19, 0xffff0000, v20
	v_lshlrev_b32_e32 v20, 16, v21
	v_and_b32_e32 v21, 0xffff0000, v21
	s_waitcnt vmcnt(1)
	v_lshlrev_b32_e32 v22, 16, v24
	v_and_b32_e32 v23, 0xffff0000, v24
	v_lshlrev_b32_e32 v24, 16, v25
	v_and_b32_e32 v25, 0xffff0000, v25
	s_waitcnt vmcnt(0)
	v_lshlrev_b32_e32 v26, 16, v28
	v_and_b32_e32 v27, 0xffff0000, v28
	v_lshlrev_b32_e32 v28, 16, v29
	v_and_b32_e32 v29, 0xffff0000, v29
	global_store_dwordx4 v[30:31], v[6:9], off
	global_store_dwordx4 v[30:31], v[10:13], off offset:1024
	global_store_dwordx4 v[30:31], v[14:17], off offset:2048
	global_store_dwordx4 v[30:31], v[18:21], off offset:3072
	global_store_dwordx4 v[32:33], v[22:25], off
	global_store_dwordx4 v[32:33], v[26:29], off offset:1024
	s_cbranch_scc0 .LBB0_558
